# dense attention loops: next K/V tile global loads issued in the previous iteration's PV (MFMA, high-priority) phase instead of the loop top
# speedup vs baseline: 1.0447x; 1.0053x over previous
; template <int DQK, bool BAND, int QT> ...
;     ...
;   const int tid = tid_(), lane = tid & 63, w = tid >> 6, h = lane >> 5, ql = lane & 31;
;   float* bias_l = (float*)(lds + 2 * ST);
;   if (BAND) { if (tid < 129) bias_l[tid] = bias_g[tid]; }
;   bf16x8 qf[QT][NKS];
; #pragma unroll
;   for (int qt = 0; qt < QT; ++qt)
; #pragma unroll
;     for (int ks = 0; ks < NKS; ++ks) qf[qt][ks] = *(const bf16x8*)(Q + (size_t)(w * WQ + qt * 32 + ql) * DQK + ks * 16 + h * 8);
;   f32x16 o[2][QT];
; #pragma unroll
;   for (int a = 0; a < 2; ++a)
; #pragma unroll
;     for (int b = 0; b < QT; ++b)
; #pragma unroll
;       for (int r = 0; r < 16; ++r) o[a][b][r] = 0.f;
;   float m[QT], l[QT];
; #pragma unroll
;   for (int qt = 0; qt < QT; ++qt) { m[qt] = -1e30f; l[qt] = 0.f; }
;   u32x4 rk[NKL], rv[2];
;   const int vrow0 = tid >> 3, vch = tid & 7;
;   unsigned klds[NKL];
; #pragma unroll
;   for (int i = 0; i < NKL; ++i) { const int idx = tid + i * 256, kr = idx / KV4, kc = idx - kr * KV4; klds[i] = kr * KROW + kc * 16; }
;   const unsigned koff0 = (unsigned)tid * 16u;
;   const unsigned voff0 = (unsigned)(vrow0 * ldv + vch * 8) * 2u, vstep = (unsigned)(32 * ldv) * 2u;
;   const unsigned vlds0 = KST + vrow0 * LROW + vch * 16;
;   auto gload = [&](int kt) {
;     const char* kb = (const char*)Kp + (size_t)kt * (DQK * 2);
;     const char* vb = (const char*)Vt + (size_t)kt * 2;
; #pragma unroll
;     for (int i = 0; i < NKL; ++i) rk[i] = *(const u32x4*)(kb + (koff0 + i * 4096u));
; #pragma unroll
;     for (int i = 0; i < 2; ++i) rv[i] = *(const u32x4*)(vb + (voff0 + i * vstep));
;   };
;   auto lstore = [&](char* st) {
; #pragma unroll
;     for (int i = 0; i < NKL; ++i) *(u32x4*)(st + klds[i]) = rk[i];
; #pragma unroll
;     for (int i = 0; i < 2; ++i) *(u32x4*)(st + vlds0 + i * 32 * LROW) = rv[i];
;   };
;   gload(kbeg);
;   lstore(lds);
;   __syncthreads();
;   const int pr = (ql & ~12) | ((ql & 4) << 1) | ((ql & 8) >> 1);
;   const int k_rd = pr * KROW + h * 16;
;   const int v_rd = KST + ql * LROW + h * 16;
;   const int qw0 = q0 + w * WQ;
;   int it = 0;
;   for (int kt = kbeg; kt < kend; kt += 64, ++it) {
;     const char* st = lds + (it & 1) * ST;
;     const bool more = (kt + 64 < kend);
;     if (more) gload(kt + 64);
; DI void phase_attn(const Ctx& c) {
;     ...
;       const int hq = i2 & 7, rest = i2 >> 3, seq = rest / nqb, qb = rest - seq * nqb;
.LBB0_826:
	s_and_b64 vcc, exec, s[0:1]
	s_cbranch_vccz .LBB0_838
	v_readlane_b32 s0, v249, 58
	s_sub_i32 s0, s26, s0
	s_ashr_i32 s1, s0, 3
	s_ashr_i32 s7, s0, 31
	s_abs_i32 s0, s1
	v_readlane_b32 s2, v248, 3
	s_mul_hi_u32 s2, s0, s2
	v_readlane_b32 s5, v248, 2
	s_mul_i32 s3, s2, s5
	s_sub_i32 s0, s0, s3
	s_add_i32 s3, s2, 1
	s_sub_i32 s4, s0, s5
	s_cmp_ge_u32 s0, s5
	s_cselect_b32 s2, s3, s2
	s_cselect_b32 s0, s4, s0
	s_add_i32 s3, s2, 1
	s_cmp_ge_u32 s0, s5
	s_cselect_b32 s0, s3, s2
	s_xor_b32 s40, s0, s7
	s_sub_i32 s0, s40, s7
	s_lshl_b32 s2, s0, s60
	s_sub_i32 s1, s1, s2
	s_lshl_b32 s2, s0, 3
	v_readlane_b32 s3, v249, 31
	s_or_b32 s2, s2, s3
	s_lshl_b32 s4, s0, 1
	v_readlane_b32 s41, v250, 44
	s_ashr_i32 s3, s2, 31
	s_or_b32 s26, s4, s41
	s_lshl_b32 s4, s1, 8
	s_lshl_b64 s[2:3], s[2:3], s20
	s_ashr_i32 s27, s26, 31
	s_ashr_i32 s5, s4, 31
	s_add_u32 s2, s2, s4
	s_addc_u32 s3, s3, s5
	s_lshl_b64 s[2:3], s[2:3], 7
	v_readlane_b32 s1, v250, 53
	s_add_u32 s34, s1, s2
	v_readlane_b32 s1, v250, 54
	s_addc_u32 s35, s1, s3
	v_readlane_b32 s1, v248, 1
	s_lshl_b64 s[2:3], s[26:27], s1
	v_readlane_b32 s1, v250, 55
	s_add_u32 s38, s1, s2
	v_readlane_b32 s1, v250, 56
	v_mov_b32_e32 v5, v199
	s_addc_u32 s39, s1, s3
	v_readlane_b32 s1, v249, 61
	v_readlane_b32 s6, v249, 63
	v_lshlrev_b32_e32 v2, 4, v5
	v_ashrrev_i32_e32 v18, 3, v5
	s_mul_hi_i32 s27, s26, s1
	s_mul_i32 s26, s26, s1
	v_and_b32_e32 v4, 0x70, v2
	v_mul_lo_u32 v0, v18, s6
	v_bfe_u32 v196, v5, 5, 1
	v_and_b32_e32 v180, 0xffffffdf, v5
	s_lshl_b64 s[26:27], s[26:27], 1
	v_readlane_b32 s42, v250, 28
	v_or_b32_e32 v6, v4, v0
	s_waitcnt vmcnt(16)
	v_or_b32_e32 v178, 32, v5
	v_lshlrev_b32_e32 v0, 4, v196
	v_ashrrev_i32_e32 v181, 31, v180
	v_readlane_b32 s43, v250, 29
	s_add_u32 s26, s42, s26
	v_ashrrev_i32_e32 v179, 31, v178
	v_lshlrev_b64 v[12:13], 7, v[180:181]
	v_lshl_add_u64 v[16:17], s[34:35], 0, v[0:1]
	s_addc_u32 s27, s43, s27
	v_lshlrev_b64 v[14:15], 7, v[178:179]
	v_lshl_add_u64 v[12:13], v[16:17], 0, v[12:13]
	v_add_u32_e32 v8, 0x1000, v2
	global_load_dwordx4 v[130:133], v2, s[38:39]
	global_load_dwordx4 v[134:137], v8, s[38:39]
	v_add_u32_e32 v10, s1, v6
	global_load_dwordx4 v[138:141], v6, s[26:27]
	global_load_dwordx4 v[142:145], v10, s[26:27]
	v_lshl_add_u64 v[14:15], v[16:17], 0, v[14:15]
	global_load_dwordx4 v[146:149], v[12:13], off
	global_load_dwordx4 v[150:153], v[12:13], off offset:32
	global_load_dwordx4 v[154:157], v[12:13], off offset:64
	global_load_dwordx4 v[158:161], v[12:13], off offset:96
	global_load_dwordx4 v[162:165], v[14:15], off
	global_load_dwordx4 v[166:169], v[14:15], off offset:32
	global_load_dwordx4 v[170:173], v[14:15], off offset:64
	global_load_dwordx4 v[174:177], v[14:15], off offset:96
	v_ashrrev_i32_e32 v19, 31, v5
	v_add_u32_e32 v20, 0x100, v5
	v_lshrrev_b32_e32 v13, 29, v19
	v_ashrrev_i32_e32 v14, 31, v20
	v_add_u32_e32 v13, v5, v13
	v_lshrrev_b32_e32 v14, 29, v14
	v_mad_u64_u32 v[182:183], s[26:27], v18, s16, v[4:5]
	v_ashrrev_i32_e32 v13, 3, v13
	v_add_u32_e32 v4, v20, v14
	v_lshlrev_b32_e32 v16, 7, v13
	v_ashrrev_i32_e32 v17, 3, v4
	v_lshlrev_b32_e32 v15, 4, v20
	v_sub_u32_e32 v4, v2, v16
	v_lshlrev_b32_e32 v16, 7, v17
	v_mad_u64_u32 v[184:185], s[26:27], v13, s16, v[4:5]
	v_sub_u32_e32 v4, v15, v16
	v_mad_u64_u32 v[186:187], s[26:27], v17, s16, v[4:5]
	s_lshl_b32 s26, s40, 1
	s_or_b32 s26, s41, s26
	s_lshl_b32 s7, s7, 1
	s_sub_i32 s7, s26, s7
	v_readlane_b32 s26, v248, 4
	v_and_b32_e32 v12, 31, v5
	v_add_u32_e32 v4, 0, v184
	s_mul_hi_i32 s27, s26, s7
	s_mul_i32 s7, s26, s7
	v_add_u32_e32 v14, 0, v182
	v_add_u32_e32 v13, 0, v186
	v_mul_u32_u24_e32 v183, 0x90, v12
	v_lshlrev_b32_e32 v12, 1, v5
	s_add_u32 s26, s7, 0x179d5980
	s_waitcnt vmcnt(11)
	ds_write_b128 v4, v[130:133]
	s_waitcnt vmcnt(10)
	ds_write_b128 v13, v[134:137]
	s_waitcnt vmcnt(9)
	ds_write_b128 v14, v[138:141] offset:9216
	s_waitcnt vmcnt(8)
	ds_write_b128 v14, v[142:145] offset:13824
	v_and_b32_e32 v4, 19, v5
	v_lshrrev_b32_e32 v5, 1, v5
	v_and_b32_e32 v12, 8, v12
	v_and_b32_e32 v5, 4, v5
	s_addc_u32 s27, s27, 0
	v_or3_b32 v4, v4, v12, v5
	v_cmp_lt_i32_e32 vcc, v221, v220
	s_add_u32 s2, s2, 0x175d7900
	v_mov_b32_e32 v3, v1
	v_mov_b32_e32 v9, v1
	v_mov_b32_e32 v7, v1
	v_mov_b32_e32 v11, v1
	v_mul_u32_u24_e32 v185, 0x90, v4
	v_cndmask_b32_e32 v4, v219, v221, vcc
	s_addc_u32 s3, s3, 0
	v_mov_b32_e32 v50, v1
	v_mov_b32_e32 v51, v1
	v_lshlrev_b32_e32 v179, 2, v4
	v_lshl_add_u64 v[188:189], s[26:27], 0, v[6:7]
	v_lshl_add_u64 v[190:191], s[26:27], 0, v[10:11]
	v_lshl_add_u64 v[192:193], s[2:3], 0, v[2:3]
	v_lshl_add_u64 v[194:195], s[2:3], 0, v[8:9]
	v_mov_b32_e32 v52, v1
	v_mov_b32_e32 v53, v1
	v_mov_b32_e32 v54, v1
	v_mov_b32_e32 v55, v1
	v_mov_b32_e32 v56, v1
	v_mov_b32_e32 v57, v1
	v_mov_b32_e32 v58, v1
	v_mov_b32_e32 v59, v1
	v_mov_b32_e32 v60, v1
	v_mov_b32_e32 v61, v1
	v_mov_b32_e32 v62, v1
	v_mov_b32_e32 v63, v1
	v_mov_b32_e32 v64, v1
	v_mov_b32_e32 v65, v1
	v_mov_b64_e32 v[18:19], v[50:51]
	v_mov_b64_e32 v[34:35], v[50:51]
	v_mov_b64_e32 v[2:3], v[50:51]
	s_mov_b32 s1, 0
	s_mov_b32 s6, 64
	v_mov_b32_e32 v197, 0xf149f2ca
	v_mov_b32_e32 v187, 0
	v_mov_b32_e32 v181, 0
	v_mov_b32_e32 v202, 0xf149f2ca
	v_mov_b64_e32 v[20:21], v[52:53]
	v_mov_b64_e32 v[22:23], v[54:55]
	v_mov_b64_e32 v[24:25], v[56:57]
	v_mov_b64_e32 v[26:27], v[58:59]
	v_mov_b64_e32 v[28:29], v[60:61]
	v_mov_b64_e32 v[30:31], v[62:63]
	v_mov_b64_e32 v[32:33], v[64:65]
	v_mov_b64_e32 v[36:37], v[52:53]
	v_mov_b64_e32 v[38:39], v[54:55]
	v_mov_b64_e32 v[40:41], v[56:57]
	v_mov_b64_e32 v[42:43], v[58:59]
	v_mov_b64_e32 v[44:45], v[60:61]
	v_mov_b64_e32 v[46:47], v[62:63]
	v_mov_b64_e32 v[48:49], v[64:65]
	v_mov_b64_e32 v[4:5], v[52:53]
	v_mov_b64_e32 v[6:7], v[54:55]
	v_mov_b64_e32 v[8:9], v[56:57]
	v_mov_b64_e32 v[10:11], v[58:59]
	v_mov_b64_e32 v[12:13], v[60:61]
	v_mov_b64_e32 v[14:15], v[62:63]
	v_mov_b64_e32 v[16:17], v[64:65]
	v_add_u32_e32 v185, v185, v0
	v_add_u32_e32 v183, v183, v0
	v_mbcnt_lo_u32_b32 v254, -1, 0
	v_mbcnt_hi_u32_b32 v254, -1, v254
	v_and_b32_e32 v255, 15, v254
	v_lshrrev_b32_e32 v253, 4, v254
	v_and_b32_e32 v253, 1, v253
	v_cmp_eq_u32_e32 vcc, v255, v253
	v_mov_b32_e32 v253, 0x3f803f80
	s_nop 1
	v_cndmask_b32_e32 v244, 0, v253, vcc
	v_mov_b32_e32 v245, v244
	v_mov_b32_e32 v246, v244
	v_mov_b32_e32 v247, v244
	v_mov_b32_e32 v236, 0
	v_mov_b32_e32 v237, 0
	v_mov_b32_e32 v238, 0
	v_mov_b32_e32 v239, 0
	v_mov_b32_e32 v240, 0
	v_mov_b32_e32 v241, 0
	v_mov_b32_e32 v242, 0
	v_mov_b32_e32 v243, 0
	s_waitcnt vmcnt(0) lgkmcnt(0)
	s_cmp_lt_u32 s6, s19
	s_cselect_b64 s[2:3], -1, 0
	s_cbranch_scc0 .Lgqa_noload0
	v_lshl_add_u64 v[254:255], s[94:95], 0, v[192:193]
	global_load_dwordx4 v[130:133], v[254:255], off
	v_lshl_add_u64 v[254:255], s[94:95], 0, v[194:195]
	global_load_dwordx4 v[134:137], v[254:255], off
	v_lshl_add_u64 v[254:255], s[94:95], 0, v[188:189]
	global_load_dwordx4 v[138:141], v[254:255], off
	v_lshl_add_u64 v[254:255], s[94:95], 0, v[190:191]
	global_load_dwordx4 v[142:145], v[254:255], off
; #define MFMA(a, b, c) __builtin_amdgcn_mfma_f32_32x32x16_bf16((a), (b), (c), 0, 0, 0)
; template <int DQK, bool BAND, int QT> ...
;     ...
;       f32x16 s[2][QT];
; #pragma unroll
;       for (int a = 0; a < 2; ++a)
; #pragma unroll
;         for (int b = 0; b < QT; ++b)
; #pragma unroll
;           for (int r = 0; r < 16; ++r) s[a][b][r] = 0.f;
; #pragma unroll
;       for (int ks = 0; ks < NKS; ++ks) {
;         const bf16x8 k0 = *(const bf16x8*)(st + k_rd + ks * 32);
;         const bf16x8 k1 = *(const bf16x8*)(st + k_rd + 32 * KROW + ks * 32);
; #pragma unroll
;         for (int qt = 0; qt < QT; ++qt) {
;           s[0][qt] = MFMA(k0, qf[qt][ks], s[0][qt]);
;           s[1][qt] = MFMA(k1, qf[qt][ks], s[1][qt]);
;         }
;       }
;       __builtin_amdgcn_s_setprio(3);
;       bf16x8 pf[QT][4];
;       const float cc = BAND ? 1.0f : scale_log2;
;       const float th = BAND ? 8.0f : 8.0f / scale_log2;
; #pragma unroll
;       for (int qt = 0; qt < QT; ++qt) {
;         if (BAND) {
; #pragma unroll
;           for (int a = 0; a < 2; ++a)
; #pragma unroll
;             for (int r = 0; r < 16; ++r) {
;               const int kidx = kt + 32 * a + (r & 7) + 8 * h + 16 * (r >> 3);
;               const int rel = kidx - (qw0 + qt * 32 + ql);
;               const bool ok = (rel >= -64) && (rel <= 64);
;               const int bi = ok ? rel + 64 : 0;
;               s[a][qt][r] = ok ? fmaf(s[a][qt][r], scale_log2, bias_l[bi]) : -1e30f;
;             }
;         }
;         float mx = s[0][qt][0];
; #pragma unroll
;         for (int r = 1; r < 16; ++r) mx = fmaxf(mx, s[0][qt][r]);
; #pragma unroll
;         for (int r = 0; r < 16; ++r) mx = fmaxf(mx, s[1][qt][r]);
;         mx = fmaxf(mx, __shfl_xor(mx, 32));
;         if (__builtin_amdgcn_ballot_w64(mx > m[qt] + th) != 0) {
;           const float mn = fmaxf(m[qt], mx);
;           const float alpha = __builtin_amdgcn_exp2f((m[qt] - mn) * cc);
;           m[qt] = mn;
;           l[qt] *= alpha;
; #pragma unroll
;           for (int r = 0; r < 16; ++r) { o[0][qt][r] *= alpha; o[1][qt][r] *= alpha; }
;         }
.Lgqa_noload0:
	v_lshl_add_u64 v[192:193], v[192:193], 0, s[88:89]
	v_lshl_add_u64 v[194:195], v[194:195], 0, s[88:89]
	v_lshl_add_u64 v[188:189], v[188:189], 0, s[76:77]
	v_lshl_add_u64 v[190:191], v[190:191], 0, s[76:77]
	s_barrier
.Lgqa_top:
	ds_read_b128 v[206:209], v185
	ds_read_b128 v[210:213], v185 offset:4608
	ds_read_b128 v[214:217], v185 offset:32
	ds_read_b128 v[232:235], v185 offset:4640
	s_waitcnt lgkmcnt(3)
	v_mfma_f32_32x32x16_bf16 v[82:97], v[206:209], v[146:149], 0
	v_mfma_f32_32x32x16_bf16 v[114:129], v[206:209], v[162:165], 0
	ds_read_b128 v[206:209], v185 offset:64
	s_waitcnt lgkmcnt(3)
	v_mfma_f32_32x32x16_bf16 v[66:81], v[210:213], v[146:149], 0
	v_mfma_f32_32x32x16_bf16 v[98:113], v[210:213], v[162:165], 0
	ds_read_b128 v[210:213], v185 offset:4672
	s_waitcnt lgkmcnt(3)
	v_mfma_f32_32x32x16_bf16 v[82:97], v[214:217], v[150:153], v[82:97]
	v_mfma_f32_32x32x16_bf16 v[114:129], v[214:217], v[166:169], v[114:129]
	ds_read_b128 v[214:217], v185 offset:96
	s_waitcnt lgkmcnt(3)
	v_mfma_f32_32x32x16_bf16 v[66:81], v[232:235], v[150:153], v[66:81]
	v_mfma_f32_32x32x16_bf16 v[98:113], v[232:235], v[166:169], v[98:113]
	ds_read_b128 v[232:235], v185 offset:4704
	s_waitcnt lgkmcnt(3)
	v_mfma_f32_32x32x16_bf16 v[82:97], v[206:209], v[154:157], v[82:97]
	v_mfma_f32_32x32x16_bf16 v[114:129], v[206:209], v[170:173], v[114:129]
	s_waitcnt lgkmcnt(2)
	v_mfma_f32_32x32x16_bf16 v[66:81], v[210:213], v[154:157], v[66:81]
	v_mfma_f32_32x32x16_bf16 v[98:113], v[210:213], v[170:173], v[98:113]
	s_waitcnt lgkmcnt(1)
	v_mfma_f32_32x32x16_bf16 v[82:97], v[214:217], v[158:161], v[82:97]
	v_mfma_f32_32x32x16_bf16 v[114:129], v[214:217], v[174:177], v[114:129]
	s_waitcnt lgkmcnt(0)
	v_mfma_f32_32x32x16_bf16 v[66:81], v[232:235], v[158:161], v[66:81]
	v_mfma_f32_32x32x16_bf16 v[98:113], v[232:235], v[174:177], v[98:113]
	s_waitcnt vmcnt(0)
	s_nop 7
	s_setprio 0
	v_max_f32_e32 v203, v82, v83
	v_max_f32_e32 v253, v114, v115
	v_max3_f32 v203, v203, v84, v85
	v_max3_f32 v253, v253, v116, v117
	v_max3_f32 v203, v203, v86, v87
	v_max3_f32 v253, v253, v118, v119
	v_max3_f32 v203, v203, v88, v89
	v_max3_f32 v253, v253, v120, v121
	v_max3_f32 v203, v203, v90, v91
	v_max3_f32 v253, v253, v122, v123
	v_max3_f32 v203, v203, v92, v93
	v_max3_f32 v253, v253, v124, v125
	v_max3_f32 v203, v203, v94, v95
	v_max3_f32 v253, v253, v126, v127
	v_max3_f32 v203, v203, v96, v97
	v_max3_f32 v253, v253, v128, v129
	v_max3_f32 v203, v203, v66, v67
	v_max3_f32 v253, v253, v98, v99
	v_max3_f32 v203, v203, v68, v69
	v_max3_f32 v253, v253, v100, v101
	v_max3_f32 v203, v203, v70, v71
	v_max3_f32 v253, v253, v102, v103
	v_max3_f32 v203, v203, v72, v73
	v_max3_f32 v253, v253, v104, v105
	v_max3_f32 v203, v203, v74, v75
	v_max3_f32 v253, v253, v106, v107
	v_max3_f32 v203, v203, v76, v77
	v_max3_f32 v253, v253, v108, v109
	v_max3_f32 v203, v203, v78, v79
	v_max3_f32 v253, v253, v110, v111
	v_max3_f32 v203, v203, v80, v81
	v_max3_f32 v253, v253, v112, v113
	v_add_f32_e32 v254, 0x42317218, v197
	v_cmp_gt_f32_e32 vcc, v203, v254
	s_cbranch_vccz .Lgqa_nr0
	ds_bpermute_b32 v254, v179, v203
	s_waitcnt lgkmcnt(0)
	v_max_f32_e32 v254, v254, v254
	v_max_f32_e32 v203, v203, v254
	v_max_f32_e32 v254, v197, v197
	v_max_f32_e32 v203, v254, v203
	v_sub_f32_e32 v197, v197, v203
	v_mul_f32_e32 v197, 0x3e38aa3b, v197
	v_exp_f32_e32 v254, v197
	v_mov_b32_e32 v197, v203
	v_pk_mul_f32 v[64:65], v[64:65], v[254:255] op_sel_hi:[1,0]
	v_pk_mul_f32 v[62:63], v[62:63], v[254:255] op_sel_hi:[1,0]
	v_pk_mul_f32 v[60:61], v[60:61], v[254:255] op_sel_hi:[1,0]
	v_pk_mul_f32 v[58:59], v[58:59], v[254:255] op_sel_hi:[1,0]
	v_pk_mul_f32 v[56:57], v[56:57], v[254:255] op_sel_hi:[1,0]
	v_pk_mul_f32 v[54:55], v[54:55], v[254:255] op_sel_hi:[1,0]
	v_pk_mul_f32 v[52:53], v[52:53], v[254:255] op_sel_hi:[1,0]
	v_pk_mul_f32 v[50:51], v[50:51], v[254:255] op_sel_hi:[1,0]
	v_pk_mul_f32 v[48:49], v[48:49], v[254:255] op_sel_hi:[1,0]
	v_pk_mul_f32 v[46:47], v[46:47], v[254:255] op_sel_hi:[1,0]
	v_pk_mul_f32 v[44:45], v[44:45], v[254:255] op_sel_hi:[1,0]
	v_pk_mul_f32 v[42:43], v[42:43], v[254:255] op_sel_hi:[1,0]
	v_pk_mul_f32 v[40:41], v[40:41], v[254:255] op_sel_hi:[1,0]
	v_pk_mul_f32 v[38:39], v[38:39], v[254:255] op_sel_hi:[1,0]
	v_pk_mul_f32 v[36:37], v[36:37], v[254:255] op_sel_hi:[1,0]
	v_pk_mul_f32 v[34:35], v[34:35], v[254:255] op_sel_hi:[1,0]
	v_pk_mul_f32 v[240:241], v[240:241], v[254:255] op_sel_hi:[1,0]
	v_pk_mul_f32 v[242:243], v[242:243], v[254:255] op_sel_hi:[1,0]

; #define MFMA(a, b, c) __builtin_amdgcn_mfma_f32_32x32x16_bf16((a), (b), (c), 0, 0, 0)
; DI unsigned pk2(float a, float b) { f32x2 v = {a, b}; bf16x2_t r = __builtin_convertvector(v, bf16x2_t); return __builtin_bit_cast(unsigned, r); }
; template <int DQK, bool BAND, int QT> ...
;     ...
;         const float mc = -m[qt] * cc;
;         float ls = 0.f;
; #pragma unroll
;         for (int a = 0; a < 2; ++a) {
; #pragma unroll
;           for (int r = 0; r < 16; ++r) { const float pv = __builtin_amdgcn_exp2f(fmaf(s[a][qt][r], cc, mc)); s[a][qt][r] = pv; ls += pv; }
; #pragma unroll
;           for (int s2 = 0; s2 < 2; ++s2) {
;             u32x4 pk;
;             pk.x = pk2(s[a][qt][8 * s2 + 0], s[a][qt][8 * s2 + 1]);
;             pk.y = pk2(s[a][qt][8 * s2 + 2], s[a][qt][8 * s2 + 3]);
;             pk.z = pk2(s[a][qt][8 * s2 + 4], s[a][qt][8 * s2 + 5]);
;             pk.w = pk2(s[a][qt][8 * s2 + 6], s[a][qt][8 * s2 + 7]);
;             pf[qt][a * 2 + s2] = __builtin_bit_cast(bf16x8, pk);
;           }
;         }
;         l[qt] += ls;
;       }
;       __builtin_amdgcn_s_setprio(0);
;       if (more) lstore(lds + ((it + 1) & 1) * ST);
; #pragma unroll
;       for (int ks = 0; ks < 4; ++ks) {
;         const bf16x8 v0 = *(const bf16x8*)(st + v_rd + ks * 32);
;         const bf16x8 v1 = *(const bf16x8*)(st + v_rd + 32 * LROW + ks * 32);
; #pragma unroll
;         for (int qt = 0; qt < QT; ++qt) {
;           o[0][qt] = MFMA(v0, pf[qt][ks], o[0][qt]);
;           o[1][qt] = MFMA(v1, pf[qt][ks], o[1][qt]);
;         }
;       }
.Lgqa_nostage:
	v_mul_f32_e32 v254, 0xbe38aa3b, v197
	v_mul_f32_e32 v255, 0xbe38aa3b, v202
	v_fmamk_f32 v82, v82, 0x3e38aa3b, v254
	v_fmamk_f32 v114, v114, 0x3e38aa3b, v255
	v_fmamk_f32 v83, v83, 0x3e38aa3b, v254
	v_fmamk_f32 v115, v115, 0x3e38aa3b, v255
	v_fmamk_f32 v84, v84, 0x3e38aa3b, v254
	v_fmamk_f32 v116, v116, 0x3e38aa3b, v255
	v_fmamk_f32 v85, v85, 0x3e38aa3b, v254
	v_fmamk_f32 v117, v117, 0x3e38aa3b, v255
	v_fmamk_f32 v86, v86, 0x3e38aa3b, v254
	v_fmamk_f32 v118, v118, 0x3e38aa3b, v255
	v_fmamk_f32 v87, v87, 0x3e38aa3b, v254
	v_fmamk_f32 v119, v119, 0x3e38aa3b, v255
	v_fmamk_f32 v88, v88, 0x3e38aa3b, v254
	v_fmamk_f32 v120, v120, 0x3e38aa3b, v255
	v_fmamk_f32 v89, v89, 0x3e38aa3b, v254
	v_fmamk_f32 v121, v121, 0x3e38aa3b, v255
	v_exp_f32_e32 v82, v82
	v_exp_f32_e32 v114, v114
	v_exp_f32_e32 v83, v83
	v_exp_f32_e32 v115, v115
	v_exp_f32_e32 v84, v84
	v_exp_f32_e32 v116, v116
	v_exp_f32_e32 v85, v85
	v_exp_f32_e32 v117, v117
	v_exp_f32_e32 v86, v86
	v_exp_f32_e32 v118, v118
	v_exp_f32_e32 v87, v87
	v_exp_f32_e32 v119, v119
	v_exp_f32_e32 v88, v88
	v_exp_f32_e32 v120, v120
	v_exp_f32_e32 v89, v89
	v_exp_f32_e32 v121, v121
	v_fmamk_f32 v90, v90, 0x3e38aa3b, v254
	v_fmamk_f32 v122, v122, 0x3e38aa3b, v255
	v_fmamk_f32 v91, v91, 0x3e38aa3b, v254
	v_fmamk_f32 v123, v123, 0x3e38aa3b, v255
	v_fmamk_f32 v92, v92, 0x3e38aa3b, v254
	v_fmamk_f32 v124, v124, 0x3e38aa3b, v255
	v_fmamk_f32 v93, v93, 0x3e38aa3b, v254
	v_fmamk_f32 v125, v125, 0x3e38aa3b, v255
	v_fmamk_f32 v94, v94, 0x3e38aa3b, v254
	v_fmamk_f32 v126, v126, 0x3e38aa3b, v255
	v_fmamk_f32 v95, v95, 0x3e38aa3b, v254
	v_fmamk_f32 v127, v127, 0x3e38aa3b, v255
	v_fmamk_f32 v96, v96, 0x3e38aa3b, v254
	v_fmamk_f32 v128, v128, 0x3e38aa3b, v255
	v_fmamk_f32 v97, v97, 0x3e38aa3b, v254
	v_fmamk_f32 v129, v129, 0x3e38aa3b, v255
	v_exp_f32_e32 v90, v90
	v_exp_f32_e32 v122, v122
	v_exp_f32_e32 v91, v91
	v_exp_f32_e32 v123, v123
	v_exp_f32_e32 v92, v92
	v_exp_f32_e32 v124, v124
	v_exp_f32_e32 v93, v93
	v_exp_f32_e32 v125, v125
	v_exp_f32_e32 v94, v94
	v_exp_f32_e32 v126, v126
	v_exp_f32_e32 v95, v95
	v_exp_f32_e32 v127, v127
	v_exp_f32_e32 v96, v96
	v_exp_f32_e32 v128, v128
	v_exp_f32_e32 v97, v97
	v_exp_f32_e32 v129, v129
	v_cvt_pk_bf16_f32 v82, v82, v83
	v_cvt_pk_bf16_f32 v114, v114, v115
	v_cvt_pk_bf16_f32 v83, v84, v85
	v_cvt_pk_bf16_f32 v115, v116, v117
	v_cvt_pk_bf16_f32 v84, v86, v87
	v_cvt_pk_bf16_f32 v116, v118, v119
	v_cvt_pk_bf16_f32 v85, v88, v89
	v_cvt_pk_bf16_f32 v117, v120, v121
	v_fmamk_f32 v66, v66, 0x3e38aa3b, v254
	v_fmamk_f32 v98, v98, 0x3e38aa3b, v255
	v_fmamk_f32 v67, v67, 0x3e38aa3b, v254
	v_fmamk_f32 v99, v99, 0x3e38aa3b, v255
	v_fmamk_f32 v68, v68, 0x3e38aa3b, v254
	v_fmamk_f32 v100, v100, 0x3e38aa3b, v255
	v_fmamk_f32 v69, v69, 0x3e38aa3b, v254
	v_fmamk_f32 v101, v101, 0x3e38aa3b, v255
	v_fmamk_f32 v70, v70, 0x3e38aa3b, v254
	v_fmamk_f32 v102, v102, 0x3e38aa3b, v255
	v_fmamk_f32 v71, v71, 0x3e38aa3b, v254
	v_fmamk_f32 v103, v103, 0x3e38aa3b, v255
	v_fmamk_f32 v72, v72, 0x3e38aa3b, v254
	v_fmamk_f32 v104, v104, 0x3e38aa3b, v255
	v_fmamk_f32 v73, v73, 0x3e38aa3b, v254
	v_fmamk_f32 v105, v105, 0x3e38aa3b, v255
	v_exp_f32_e32 v66, v66
	v_exp_f32_e32 v98, v98
	v_exp_f32_e32 v67, v67
	v_exp_f32_e32 v99, v99
	v_exp_f32_e32 v68, v68
	v_exp_f32_e32 v100, v100
	v_exp_f32_e32 v69, v69
	v_exp_f32_e32 v101, v101
	v_exp_f32_e32 v70, v70
	v_exp_f32_e32 v102, v102
	v_exp_f32_e32 v71, v71
	v_exp_f32_e32 v103, v103
	v_exp_f32_e32 v72, v72
	v_exp_f32_e32 v104, v104
	v_exp_f32_e32 v73, v73
	v_exp_f32_e32 v105, v105
	v_cvt_pk_bf16_f32 v90, v90, v91
	v_cvt_pk_bf16_f32 v122, v122, v123
	v_cvt_pk_bf16_f32 v91, v92, v93
	v_cvt_pk_bf16_f32 v123, v124, v125
	v_cvt_pk_bf16_f32 v92, v94, v95
	v_cvt_pk_bf16_f32 v124, v126, v127
	v_cvt_pk_bf16_f32 v93, v96, v97
	v_cvt_pk_bf16_f32 v125, v128, v129
	v_fmamk_f32 v74, v74, 0x3e38aa3b, v254
	v_fmamk_f32 v106, v106, 0x3e38aa3b, v255
	v_fmamk_f32 v75, v75, 0x3e38aa3b, v254
	v_fmamk_f32 v107, v107, 0x3e38aa3b, v255
	v_fmamk_f32 v76, v76, 0x3e38aa3b, v254
	v_fmamk_f32 v108, v108, 0x3e38aa3b, v255
	v_fmamk_f32 v77, v77, 0x3e38aa3b, v254
	v_fmamk_f32 v109, v109, 0x3e38aa3b, v255
	v_fmamk_f32 v78, v78, 0x3e38aa3b, v254
	v_fmamk_f32 v110, v110, 0x3e38aa3b, v255
	v_fmamk_f32 v79, v79, 0x3e38aa3b, v254
	v_fmamk_f32 v111, v111, 0x3e38aa3b, v255
	v_fmamk_f32 v80, v80, 0x3e38aa3b, v254
	v_fmamk_f32 v112, v112, 0x3e38aa3b, v255
	v_fmamk_f32 v81, v81, 0x3e38aa3b, v254
	v_fmamk_f32 v113, v113, 0x3e38aa3b, v255
	v_exp_f32_e32 v74, v74
	v_exp_f32_e32 v106, v106
	v_exp_f32_e32 v75, v75
	v_exp_f32_e32 v107, v107
	v_exp_f32_e32 v76, v76
	v_exp_f32_e32 v108, v108
	v_exp_f32_e32 v77, v77
	v_exp_f32_e32 v109, v109
	v_exp_f32_e32 v78, v78
	v_exp_f32_e32 v110, v110
	v_exp_f32_e32 v79, v79
	v_exp_f32_e32 v111, v111
	v_exp_f32_e32 v80, v80
	v_exp_f32_e32 v112, v112
	v_exp_f32_e32 v81, v81
	v_exp_f32_e32 v113, v113
	v_cvt_pk_bf16_f32 v66, v66, v67
	v_cvt_pk_bf16_f32 v98, v98, v99
	v_cvt_pk_bf16_f32 v67, v68, v69
	v_cvt_pk_bf16_f32 v99, v100, v101
	v_cvt_pk_bf16_f32 v68, v70, v71
	v_cvt_pk_bf16_f32 v100, v102, v103
	v_cvt_pk_bf16_f32 v69, v72, v73
	v_cvt_pk_bf16_f32 v101, v104, v105
	v_cvt_pk_bf16_f32 v74, v74, v75
	v_cvt_pk_bf16_f32 v106, v106, v107
	v_cvt_pk_bf16_f32 v75, v76, v77
	v_cvt_pk_bf16_f32 v107, v108, v109
	v_cvt_pk_bf16_f32 v76, v78, v79
	v_cvt_pk_bf16_f32 v108, v110, v111
	v_cvt_pk_bf16_f32 v77, v80, v81
	v_cvt_pk_bf16_f32 v109, v112, v113
	s_setprio 2
	ds_read_b128 v[86:89], v183 offset:9216
	ds_read_b128 v[94:97], v183 offset:13824
	ds_read_b128 v[70:73], v183 offset:9248
	ds_read_b128 v[78:81], v183 offset:13856
	ds_read_b128 v[118:121], v183 offset:9280
	ds_read_b128 v[126:129], v183 offset:13888
	ds_read_b128 v[102:105], v183 offset:9312
	ds_read_b128 v[110:113], v183 offset:13920
	s_waitcnt lgkmcnt(7)
	v_mfma_f32_32x32x16_bf16 v[50:65], v[86:89], v[82:85], v[50:65]
	v_mfma_f32_32x32x16_bf16 v[18:33], v[86:89], v[114:117], v[18:33]
	s_waitcnt lgkmcnt(6)
	v_mfma_f32_32x32x16_bf16 v[34:49], v[94:97], v[82:85], v[34:49]
	v_mfma_f32_32x32x16_bf16 v[2:17], v[94:97], v[114:117], v[2:17]
	v_mfma_f32_16x16x32_bf16 v[240:243], v[244:247], v[82:85], v[240:243]
	v_mfma_f32_16x16x32_bf16 v[236:239], v[244:247], v[114:117], v[236:239]
	s_add_i32 s7, s6, 64
	s_cmp_lt_u32 s7, s19
	s_cselect_b64 s[2:3], -1, 0
	s_cbranch_scc0 .Lgqa_noloadp
	v_lshl_add_u64 v[254:255], s[94:95], 0, v[192:193]
	global_load_dwordx4 v[130:133], v[254:255], off
	v_lshl_add_u64 v[254:255], s[94:95], 0, v[194:195]
	global_load_dwordx4 v[134:137], v[254:255], off
	v_lshl_add_u64 v[254:255], s[94:95], 0, v[188:189]
	global_load_dwordx4 v[138:141], v[254:255], off
	v_lshl_add_u64 v[254:255], s[94:95], 0, v[190:191]
	global_load_dwordx4 v[142:145], v[254:255], off
; #define MFMA(a, b, c) __builtin_amdgcn_mfma_f32_32x32x16_bf16((a), (b), (c), 0, 0, 0)
; template <int DQK, bool BAND, int QT> ...
;     ...
; #pragma unroll
;       for (int ks = 0; ks < 4; ++ks) {
;         const bf16x8 v0 = *(const bf16x8*)(st + v_rd + ks * 32);
;         const bf16x8 v1 = *(const bf16x8*)(st + v_rd + 32 * LROW + ks * 32);
; #pragma unroll
;         for (int qt = 0; qt < QT; ++qt) {
;           o[0][qt] = MFMA(v0, pf[qt][ks], o[0][qt]);
;           o[1][qt] = MFMA(v1, pf[qt][ks], o[1][qt]);
;         }
;       }
;     } else {
;       if (more) lstore(lds + ((it + 1) & 1) * ST);
;     }
;     __syncthreads();
;   }
; #pragma unroll
;   for (int qt = 0; qt < QT; ++qt) {
;     const float lt = l[qt] + __shfl_xor(l[qt], 32);
.Lgqa_noloadp:
	v_lshl_add_u64 v[192:193], v[192:193], 0, s[88:89]
	v_lshl_add_u64 v[194:195], v[194:195], 0, s[88:89]
	v_lshl_add_u64 v[188:189], v[188:189], 0, s[76:77]
	v_lshl_add_u64 v[190:191], v[190:191], 0, s[76:77]
	s_waitcnt lgkmcnt(5)
	v_mfma_f32_32x32x16_bf16 v[50:65], v[70:73], v[90:93], v[50:65]
	v_mfma_f32_32x32x16_bf16 v[18:33], v[70:73], v[122:125], v[18:33]
	s_waitcnt lgkmcnt(4)
	v_mfma_f32_32x32x16_bf16 v[34:49], v[78:81], v[90:93], v[34:49]
	v_mfma_f32_32x32x16_bf16 v[2:17], v[78:81], v[122:125], v[2:17]
	v_mfma_f32_16x16x32_bf16 v[240:243], v[244:247], v[90:93], v[240:243]
	v_mfma_f32_16x16x32_bf16 v[236:239], v[244:247], v[122:125], v[236:239]
	s_waitcnt lgkmcnt(3)
	v_mfma_f32_32x32x16_bf16 v[50:65], v[118:121], v[66:69], v[50:65]
	v_mfma_f32_32x32x16_bf16 v[18:33], v[118:121], v[98:101], v[18:33]
	s_waitcnt lgkmcnt(2)
	v_mfma_f32_32x32x16_bf16 v[34:49], v[126:129], v[66:69], v[34:49]
	v_mfma_f32_32x32x16_bf16 v[2:17], v[126:129], v[98:101], v[2:17]
	v_mfma_f32_16x16x32_bf16 v[240:243], v[244:247], v[66:69], v[240:243]
	v_mfma_f32_16x16x32_bf16 v[236:239], v[244:247], v[98:101], v[236:239]
	s_bitcmp1_b32 s1, 0
	s_cselect_b32 s7, -1, 1
	s_mulk_i32 s7, 0x4800
	v_add_u32_e32 v185, s7, v185
	v_add_u32_e32 v183, s7, v183
	s_add_i32 s1, s1, 1
	s_add_i32 s6, s6, 64
	s_waitcnt lgkmcnt(0)
	s_barrier
	v_mfma_f32_32x32x16_bf16 v[50:65], v[102:105], v[74:77], v[50:65]
	v_mfma_f32_32x32x16_bf16 v[18:33], v[102:105], v[106:109], v[18:33]
	v_mfma_f32_32x32x16_bf16 v[34:49], v[110:113], v[74:77], v[34:49]
	v_mfma_f32_32x32x16_bf16 v[2:17], v[110:113], v[106:109], v[2:17]
	v_mfma_f32_16x16x32_bf16 v[240:243], v[244:247], v[74:77], v[240:243]
	v_mfma_f32_16x16x32_bf16 v[236:239], v[244:247], v[106:109], v[236:239]
	s_cmp_lg_u32 s21, s1
	s_cbranch_scc1 .Lgqa_top
	s_setprio 0
	s_nop 7
	v_mbcnt_lo_u32_b32 v254, -1, 0
	v_mbcnt_hi_u32_b32 v254, -1, v254
	v_and_b32_e32 v255, 15, v254
	v_lshlrev_b32_e32 v255, 2, v255
	ds_bpermute_b32 v203, v255, v240
	ds_bpermute_b32 v253, v255, v241
	s_waitcnt lgkmcnt(0)
	v_cmp_gt_u32_e32 vcc, 16, v254
	s_nop 1
	v_cndmask_b32_e32 v187, v253, v203, vcc
	v_cmp_gt_u32_e32 vcc, 32, v254
	s_nop 1
	v_cndmask_b32_e32 v187, 0, v187, vcc
	ds_bpermute_b32 v203, v255, v236
	ds_bpermute_b32 v253, v255, v237
	s_waitcnt lgkmcnt(0)
	v_cmp_gt_u32_e32 vcc, 16, v254
	s_nop 1
	v_cndmask_b32_e32 v181, v253, v203, vcc
	v_cmp_gt_u32_e32 vcc, 32, v254
	s_nop 1
	v_cndmask_b32_e32 v181, 0, v181, vcc

; DI int tid_() { int t = threadIdx.x; asm volatile("" : "+v"(t)); return t; }
; template <int DQK, bool BAND, int QT> ...
;     ...
;   const int tid = tid_(), lane = tid & 63, w = tid >> 6, h = lane >> 5, ql = lane & 31;
;   float* bias_l = (float*)(lds + 2 * ST);
;   if (BAND) { if (tid < 129) bias_l[tid] = bias_g[tid]; }
;   bf16x8 qf[QT][NKS];
; #pragma unroll
;   for (int qt = 0; qt < QT; ++qt)
; #pragma unroll
;     for (int ks = 0; ks < NKS; ++ks) qf[qt][ks] = *(const bf16x8*)(Q + (size_t)(w * WQ + qt * 32 + ql) * DQK + ks * 16 + h * 8);
;   f32x16 o[2][QT];
; #pragma unroll
;   for (int a = 0; a < 2; ++a)
; #pragma unroll
;     for (int b = 0; b < QT; ++b)
; #pragma unroll
;       for (int r = 0; r < 16; ++r) o[a][b][r] = 0.f;
;   float m[QT], l[QT];
; #pragma unroll
;   for (int qt = 0; qt < QT; ++qt) { m[qt] = -1e30f; l[qt] = 0.f; }
;   u32x4 rk[NKL], rv[2];
;   const int vrow0 = tid >> 3, vch = tid & 7;
;   unsigned klds[NKL];
; #pragma unroll
;   for (int i = 0; i < NKL; ++i) { const int idx = tid + i * 256, kr = idx / KV4, kc = idx - kr * KV4; klds[i] = kr * KROW + kc * 16; }
;   const unsigned koff0 = (unsigned)tid * 16u;
;   const unsigned voff0 = (unsigned)(vrow0 * ldv + vch * 8) * 2u, vstep = (unsigned)(32 * ldv) * 2u;
;   const unsigned vlds0 = KST + vrow0 * LROW + vch * 16;
;   auto gload = [&](int kt) {
;     const char* kb = (const char*)Kp + (size_t)kt * (DQK * 2);
;     const char* vb = (const char*)Vt + (size_t)kt * 2;
; #pragma unroll
;     for (int i = 0; i < NKL; ++i) rk[i] = *(const u32x4*)(kb + (koff0 + i * 4096u));
; #pragma unroll
;     for (int i = 0; i < 2; ++i) rv[i] = *(const u32x4*)(vb + (voff0 + i * vstep));
;   };
;   auto lstore = [&](char* st) {
; #pragma unroll
;     for (int i = 0; i < NKL; ++i) *(u32x4*)(st + klds[i]) = rk[i];
; #pragma unroll
;     for (int i = 0; i < 2; ++i) *(u32x4*)(st + vlds0 + i * 32 * LROW) = rv[i];
;   };
;   gload(kbeg);
;   lstore(lds);
;   __syncthreads();
;   const int pr = (ql & ~12) | ((ql & 4) << 1) | ((ql & 8) >> 1);
;   const int k_rd = pr * KROW + h * 16;
;   const int v_rd = KST + ql * LROW + h * 16;
;   const int qw0 = q0 + w * WQ;
;   int it = 0;
;   for (int kt = kbeg; kt < kend; kt += 64, ++it) {
;     const char* st = lds + (it & 1) * ST;
;     const bool more = (kt + 64 < kend);
;     if (more) gload(kt + 64);
; DI void phase_attn(const Ctx& c) {
;     ...
;     if (item < n_mla) {
.LBB0_839:
	s_andn2_b64 vcc, exec, s[0:1]
	s_cbranch_vccnz .LBB0_664
	s_abs_i32 s0, s25
	v_readlane_b32 s1, v248, 3
	s_mul_hi_u32 s1, s0, s1
	v_readlane_b32 s4, v248, 2
	s_mul_i32 s2, s1, s4
	s_sub_i32 s0, s0, s2
	s_ashr_i32 s7, s25, 31
	s_add_i32 s2, s1, 1
	s_sub_i32 s3, s0, s4
	s_cmp_ge_u32 s0, s4
	s_cselect_b32 s1, s2, s1
	s_cselect_b32 s0, s3, s0
	s_add_i32 s2, s1, 1
	s_cmp_ge_u32 s0, s4
	s_cselect_b32 s0, s2, s1
	s_xor_b32 s38, s0, s7
	s_sub_i32 s0, s38, s7
	s_lshl_b32 s1, s0, s60
	s_lshl_b32 s2, s0, 3
	v_readlane_b32 s40, v249, 31
	s_sub_i32 s1, s25, s1
	s_or_b32 s26, s2, s40
	s_ashr_i32 s27, s26, 31
	s_lshl_b32 s4, s1, 8
	s_lshl_b64 s[34:35], s[26:27], s20
	s_ashr_i32 s5, s4, 31
	s_add_u32 s1, s34, s4
	s_addc_u32 s2, s35, s5
	s_mulk_i32 s2, 0xc0
	s_mul_hi_u32 s3, s1, 0xc0
	s_add_i32 s3, s3, s2
	s_mulk_i32 s1, 0xc0
	v_readlane_b32 s42, v250, 40
	v_readlane_b32 s43, v250, 41
	s_add_u32 s2, s42, s1
	s_mul_i32 s1, s35, 0xc0
	s_mul_hi_u32 s6, s34, 0xc0
	s_addc_u32 s3, s43, s3
	s_add_i32 s25, s6, s1
	s_mul_i32 s39, s34, 0xc0
	v_readlane_b32 s34, v250, 38
	v_readlane_b32 s35, v250, 39
	s_add_u32 s34, s34, s39
	v_mov_b32_e32 v2, v199
	s_addc_u32 s35, s35, s25
	v_readlane_b32 s1, v249, 61
	v_lshlrev_b32_e32 v4, 4, v2
	global_load_dwordx4 v[130:133], v4, s[34:35]
	v_add_u32_e32 v8, 0x1000, v4
	global_load_dwordx4 v[134:137], v8, s[34:35]
	s_mul_hi_i32 s27, s26, s1
	s_mul_i32 s26, s26, s1
	s_lshl_b64 s[26:27], s[26:27], 1
	v_readlane_b32 s42, v250, 36
	v_ashrrev_i32_e32 v3, 3, v2
	v_readlane_b32 s6, v249, 63
	v_readlane_b32 s43, v250, 37
	s_add_u32 s26, s42, s26
	v_and_b32_e32 v6, 0x70, v4
	v_mul_lo_u32 v0, v3, s6
	s_addc_u32 s27, s43, s27
	v_add_u32_e32 v10, 0x2000, v4
	v_or_b32_e32 v12, v6, v0
	v_bfe_u32 v230, v2, 5, 1
	global_load_dwordx4 v[138:141], v10, s[34:35]
	v_add_u32_e32 v14, s1, v12
	global_load_dwordx4 v[146:149], v12, s[26:27]
	global_load_dwordx4 v[170:173], v14, s[26:27]
	v_lshlrev_b32_e32 v0, 4, v230
	v_and_b32_e32 v204, 0xffffffdf, v2
	v_lshl_add_u64 v[16:17], s[2:3], 0, v[0:1]
	s_movk_i32 s1, 0xc0
	v_or_b32_e32 v202, 32, v2
	v_mad_i64_i32 v[18:19], s[2:3], v204, s1, v[16:17]
	v_mad_i64_i32 v[16:17], s[2:3], v202, s1, v[16:17]
	global_load_dwordx4 v[142:145], v[18:19], off
	global_load_dwordx4 v[150:153], v[18:19], off offset:32
	global_load_dwordx4 v[154:157], v[18:19], off offset:64
	global_load_dwordx4 v[158:161], v[18:19], off offset:96
	global_load_dwordx4 v[162:165], v[18:19], off offset:128
	global_load_dwordx4 v[166:169], v[18:19], off offset:160
	global_load_dwordx4 v[174:177], v[16:17], off
	global_load_dwordx4 v[178:181], v[16:17], off offset:32
	global_load_dwordx4 v[182:185], v[16:17], off offset:64
	global_load_dwordx4 v[186:189], v[16:17], off offset:96
	global_load_dwordx4 v[190:193], v[16:17], off offset:128
	global_load_dwordx4 v[194:197], v[16:17], off offset:160
	s_mov_b32 s1, 0x2aaaaaab
	v_mul_hi_i32 v5, v2, s1
	v_lshrrev_b32_e32 v7, 31, v5
	v_ashrrev_i32_e32 v5, 1, v5
	v_add_u32_e32 v5, v5, v7
	s_movk_i32 s6, 0xd0
	v_mad_u64_u32 v[16:17], s[2:3], v5, -12, v[2:3]
	v_mul_lo_u32 v5, v5, s6
	v_lshl_add_u32 v231, v16, 4, v5
	v_add_u32_e32 v16, 0x100, v2
	v_mul_hi_i32 v5, v16, s1
	v_lshrrev_b32_e32 v7, 31, v5
	v_ashrrev_i32_e32 v5, 1, v5
	v_add_u32_e32 v5, v5, v7
	v_mad_u64_u32 v[16:17], s[2:3], v5, -12, v[16:17]
	v_mul_lo_u32 v5, v5, s6
	v_lshl_add_u32 v232, v16, 4, v5
	v_add_u32_e32 v16, 0x200, v2
	v_mul_hi_i32 v5, v16, s1
	v_lshrrev_b32_e32 v7, 31, v5
	v_ashrrev_i32_e32 v5, 1, v5
	v_add_u32_e32 v5, v5, v7
	v_mad_u64_u32 v[16:17], s[2:3], v5, -12, v[16:17]
	v_mul_lo_u32 v5, v5, s6
	v_add_u32_e32 v7, 0, v231
	v_lshl_add_u32 v233, v16, 4, v5
	v_mov_b32_e32 v13, v1
	v_mov_b32_e32 v15, v1
	v_cmp_lt_i32_e32 vcc, v221, v220
	v_mov_b32_e32 v5, v1
	v_mov_b32_e32 v9, v1
	v_mov_b32_e32 v11, v1
	v_mov_b32_e32 v50, v1
	v_mov_b32_e32 v51, v1
	v_mov_b32_e32 v52, v1
	v_mov_b32_e32 v53, v1
	v_mov_b32_e32 v54, v1
	v_mov_b32_e32 v55, v1
	v_mov_b32_e32 v56, v1
	v_mov_b32_e32 v57, v1
	v_mov_b32_e32 v58, v1
	v_mov_b32_e32 v59, v1
	v_mov_b32_e32 v60, v1
	v_mov_b32_e32 v61, v1
	v_mov_b32_e32 v62, v1
	v_mov_b32_e32 v63, v1
	s_waitcnt vmcnt(16)
	ds_write_b128 v7, v[130:133]
	v_add_u32_e32 v7, 0, v232
	s_waitcnt vmcnt(15)
	ds_write_b128 v7, v[134:137]
	v_add_u32_e32 v7, 0, v233
	v_mad_u64_u32 v[206:207], s[2:3], v3, s16, v[6:7]
	s_lshl_b32 s2, s38, 3
	s_or_b32 s2, s40, s2
	s_lshl_b32 s3, s7, 3
	v_add_u32_e32 v3, 0, v206
	s_sub_i32 s2, s2, s3
	v_readlane_b32 s7, v248, 4
	s_mul_hi_i32 s3, s7, s2
	s_mul_i32 s2, s7, s2
	v_lshlrev_b32_e32 v6, 1, v2
	s_add_u32 s2, s2, 0x10d35980
	v_and_b32_e32 v6, 8, v6
	s_waitcnt vmcnt(14)
	ds_write_b128 v7, v[138:141]
	s_waitcnt vmcnt(13)
	ds_write_b128 v3, v[146:149] offset:13312
	s_waitcnt vmcnt(12)
	ds_write_b128 v3, v[170:173] offset:17920
	v_and_b32_e32 v3, 31, v2
	v_mul_u32_u24_e32 v234, 0x90, v3
	v_and_b32_e32 v3, 19, v2
	v_lshrrev_b32_e32 v2, 1, v2
	v_and_b32_e32 v2, 4, v2
	s_addc_u32 s3, s3, 0
	v_or3_b32 v2, v3, v6, v2
	v_lshl_add_u64 v[208:209], s[2:3], 0, v[12:13]
	v_lshl_add_u64 v[210:211], s[2:3], 0, v[14:15]
	s_add_u32 s2, s39, 0xf538900
	v_mul_u32_u24_e32 v235, 0xd0, v2
	v_cndmask_b32_e32 v2, v219, v221, vcc
	s_addc_u32 s3, s25, 0
	v_lshlrev_b32_e32 v203, 2, v2
	v_lshl_add_u64 v[212:213], s[2:3], 0, v[4:5]
	v_lshl_add_u64 v[214:215], s[2:3], 0, v[8:9]
	v_lshl_add_u64 v[216:217], s[2:3], 0, v[10:11]
	v_mov_b32_e32 v64, v1
	v_mov_b32_e32 v65, v1
	v_mov_b64_e32 v[18:19], v[50:51]
	v_mov_b64_e32 v[34:35], v[50:51]
	v_mov_b64_e32 v[2:3], v[50:51]
	s_mov_b32 s1, 0
	s_mov_b32 s6, 64
	v_mov_b32_e32 v237, 0xf149f2ca
	v_mov_b32_e32 v236, 0
	v_mov_b32_e32 v207, 0
	v_mov_b32_e32 v238, 0xf149f2ca
	v_mov_b64_e32 v[20:21], v[52:53]
	v_mov_b64_e32 v[22:23], v[54:55]
	v_mov_b64_e32 v[24:25], v[56:57]
	v_mov_b64_e32 v[26:27], v[58:59]
	v_mov_b64_e32 v[28:29], v[60:61]
	v_mov_b64_e32 v[30:31], v[62:63]
	v_mov_b64_e32 v[32:33], v[64:65]
	v_mov_b64_e32 v[36:37], v[52:53]
	v_mov_b64_e32 v[38:39], v[54:55]
	v_mov_b64_e32 v[40:41], v[56:57]
	v_mov_b64_e32 v[42:43], v[58:59]
	v_mov_b64_e32 v[44:45], v[60:61]
	v_mov_b64_e32 v[46:47], v[62:63]
	v_mov_b64_e32 v[48:49], v[64:65]
	v_mov_b64_e32 v[4:5], v[52:53]
	v_mov_b64_e32 v[6:7], v[54:55]
	v_mov_b64_e32 v[8:9], v[56:57]
	v_mov_b64_e32 v[10:11], v[58:59]
	v_mov_b64_e32 v[12:13], v[60:61]
	v_mov_b64_e32 v[14:15], v[62:63]
	v_mov_b64_e32 v[16:17], v[64:65]
	v_add_u32_e32 v235, v235, v0
	v_add_u32_e32 v234, v234, v0
	s_waitcnt vmcnt(0) lgkmcnt(0)
	s_cmp_lt_u32 s6, s19
	s_cselect_b64 s[2:3], -1, 0
	s_cbranch_scc0 .Lmla_noload0
	v_lshl_add_u64 v[254:255], s[94:95], 0, v[212:213]
	global_load_dwordx4 v[130:133], v[254:255], off
	v_lshl_add_u64 v[254:255], s[94:95], 0, v[214:215]
	global_load_dwordx4 v[134:137], v[254:255], off
	v_lshl_add_u64 v[254:255], s[94:95], 0, v[216:217]
	global_load_dwordx4 v[138:141], v[254:255], off
	v_lshl_add_u64 v[254:255], s[94:95], 0, v[208:209]
	global_load_dwordx4 v[146:149], v[254:255], off
	v_lshl_add_u64 v[254:255], s[94:95], 0, v[210:211]
	global_load_dwordx4 v[170:173], v[254:255], off
; #define MFMA(a, b, c) __builtin_amdgcn_mfma_f32_32x32x16_bf16((a), (b), (c), 0, 0, 0)
; template <int DQK, bool BAND, int QT> ...
;     ...
;       f32x16 s[2][QT];
; #pragma unroll
;       for (int a = 0; a < 2; ++a)
; #pragma unroll
;         for (int b = 0; b < QT; ++b)
; #pragma unroll
;           for (int r = 0; r < 16; ++r) s[a][b][r] = 0.f;
; #pragma unroll
;       for (int ks = 0; ks < NKS; ++ks) {
;         const bf16x8 k0 = *(const bf16x8*)(st + k_rd + ks * 32);
;         const bf16x8 k1 = *(const bf16x8*)(st + k_rd + 32 * KROW + ks * 32);
; #pragma unroll
;         for (int qt = 0; qt < QT; ++qt) {
;           s[0][qt] = MFMA(k0, qf[qt][ks], s[0][qt]);
;           s[1][qt] = MFMA(k1, qf[qt][ks], s[1][qt]);
;         }
;       }
;       __builtin_amdgcn_s_setprio(3);
;       bf16x8 pf[QT][4];
;       const float cc = BAND ? 1.0f : scale_log2;
;       const float th = BAND ? 8.0f : 8.0f / scale_log2;
; #pragma unroll
;       for (int qt = 0; qt < QT; ++qt) {
;         if (BAND) {
; #pragma unroll
;           for (int a = 0; a < 2; ++a)
; #pragma unroll
;             for (int r = 0; r < 16; ++r) {
;               const int kidx = kt + 32 * a + (r & 7) + 8 * h + 16 * (r >> 3);
;               const int rel = kidx - (qw0 + qt * 32 + ql);
;               const bool ok = (rel >= -64) && (rel <= 64);
;               const int bi = ok ? rel + 64 : 0;
;               s[a][qt][r] = ok ? fmaf(s[a][qt][r], scale_log2, bias_l[bi]) : -1e30f;
;             }
;         }
;         float mx = s[0][qt][0];
; #pragma unroll
;         for (int r = 1; r < 16; ++r) mx = fmaxf(mx, s[0][qt][r]);
; #pragma unroll
;         for (int r = 0; r < 16; ++r) mx = fmaxf(mx, s[1][qt][r]);
;         mx = fmaxf(mx, __shfl_xor(mx, 32));
;         if (__builtin_amdgcn_ballot_w64(mx > m[qt] + th) != 0) {
;           const float mn = fmaxf(m[qt], mx);
;           const float alpha = __builtin_amdgcn_exp2f((m[qt] - mn) * cc);
;           m[qt] = mn;
;           l[qt] *= alpha;
; #pragma unroll
;           for (int r = 0; r < 16; ++r) { o[0][qt][r] *= alpha; o[1][qt][r] *= alpha; }
;         }
.Lmla_noload0:
	v_lshl_add_u64 v[208:209], v[208:209], 0, s[76:77]
	v_lshl_add_u64 v[210:211], v[210:211], 0, s[76:77]
	v_lshl_add_u64 v[212:213], v[212:213], 0, s[84:85]
	v_lshl_add_u64 v[214:215], v[214:215], 0, s[84:85]
	v_lshl_add_u64 v[216:217], v[216:217], 0, s[84:85]
	s_barrier
.Lmla_top:
	ds_read_b128 v[102:105], v235
	ds_read_b128 v[98:101], v235 offset:6656
	ds_read_b128 v[240:243], v235 offset:32
	ds_read_b128 v[244:247], v235 offset:6688
	s_waitcnt lgkmcnt(3)
	v_mfma_f32_32x32x16_bf16 v[82:97], v[102:105], v[142:145], 0
	v_mfma_f32_32x32x16_bf16 v[114:129], v[102:105], v[174:177], 0
	s_waitcnt lgkmcnt(2)
	v_mfma_f32_32x32x16_bf16 v[66:81], v[98:101], v[142:145], 0
	v_mfma_f32_32x32x16_bf16 v[98:113], v[98:101], v[174:177], 0
	s_waitcnt lgkmcnt(1)
	v_mfma_f32_32x32x16_bf16 v[82:97], v[240:243], v[150:153], v[82:97]
	v_mfma_f32_32x32x16_bf16 v[114:129], v[240:243], v[178:181], v[114:129]
	ds_read_b128 v[240:243], v235 offset:64
	s_waitcnt lgkmcnt(1)
	v_mfma_f32_32x32x16_bf16 v[66:81], v[244:247], v[150:153], v[66:81]
	v_mfma_f32_32x32x16_bf16 v[98:113], v[244:247], v[178:181], v[98:113]
	ds_read_b128 v[244:247], v235 offset:6720
	s_waitcnt lgkmcnt(1)
	v_mfma_f32_32x32x16_bf16 v[82:97], v[240:243], v[154:157], v[82:97]
	v_mfma_f32_32x32x16_bf16 v[114:129], v[240:243], v[182:185], v[114:129]
	ds_read_b128 v[240:243], v235 offset:96
	s_waitcnt lgkmcnt(1)
	v_mfma_f32_32x32x16_bf16 v[66:81], v[244:247], v[154:157], v[66:81]
	v_mfma_f32_32x32x16_bf16 v[98:113], v[244:247], v[182:185], v[98:113]
	ds_read_b128 v[244:247], v235 offset:6752
	s_waitcnt lgkmcnt(1)
	v_mfma_f32_32x32x16_bf16 v[82:97], v[240:243], v[158:161], v[82:97]
	v_mfma_f32_32x32x16_bf16 v[114:129], v[240:243], v[186:189], v[114:129]
	ds_read_b128 v[240:243], v235 offset:128
	s_waitcnt lgkmcnt(1)
	v_mfma_f32_32x32x16_bf16 v[66:81], v[244:247], v[158:161], v[66:81]
	v_mfma_f32_32x32x16_bf16 v[98:113], v[244:247], v[186:189], v[98:113]
	ds_read_b128 v[244:247], v235 offset:6784
	s_waitcnt lgkmcnt(1)
	v_mfma_f32_32x32x16_bf16 v[82:97], v[240:243], v[162:165], v[82:97]
	v_mfma_f32_32x32x16_bf16 v[114:129], v[240:243], v[190:193], v[114:129]
	ds_read_b128 v[240:243], v235 offset:160
	s_waitcnt lgkmcnt(1)
	v_mfma_f32_32x32x16_bf16 v[66:81], v[244:247], v[162:165], v[66:81]
	v_mfma_f32_32x32x16_bf16 v[98:113], v[244:247], v[190:193], v[98:113]
	ds_read_b128 v[244:247], v235 offset:6816
	s_waitcnt lgkmcnt(1)
	v_mfma_f32_32x32x16_bf16 v[82:97], v[240:243], v[166:169], v[82:97]
	v_mfma_f32_32x32x16_bf16 v[114:129], v[240:243], v[194:197], v[114:129]
	s_waitcnt lgkmcnt(0)
	v_mfma_f32_32x32x16_bf16 v[66:81], v[244:247], v[166:169], v[66:81]
	v_mfma_f32_32x32x16_bf16 v[98:113], v[244:247], v[194:197], v[98:113]
	s_waitcnt vmcnt(0)
	s_nop 7
	s_setprio 0
	v_max_f32_e32 v239, v82, v83
	v_max_f32_e32 v253, v114, v115
	v_max3_f32 v239, v239, v84, v85
	v_max3_f32 v253, v253, v116, v117
	v_max3_f32 v239, v239, v86, v87
	v_max3_f32 v253, v253, v118, v119
	v_max3_f32 v239, v239, v88, v89
	v_max3_f32 v253, v253, v120, v121
	v_max3_f32 v239, v239, v90, v91
	v_max3_f32 v253, v253, v122, v123
	v_max3_f32 v239, v239, v92, v93
	v_max3_f32 v253, v253, v124, v125
	v_max3_f32 v239, v239, v94, v95
	v_max3_f32 v253, v253, v126, v127
	v_max3_f32 v239, v239, v96, v97
	v_max3_f32 v253, v253, v128, v129
	v_max3_f32 v239, v239, v66, v67
	v_max3_f32 v253, v253, v98, v99
	v_max3_f32 v239, v239, v68, v69
	v_max3_f32 v253, v253, v100, v101
	v_max3_f32 v239, v239, v70, v71
	v_max3_f32 v253, v253, v102, v103
	v_max3_f32 v239, v239, v72, v73
	v_max3_f32 v253, v253, v104, v105
	v_max3_f32 v239, v239, v74, v75
	v_max3_f32 v253, v253, v106, v107
	v_max3_f32 v239, v239, v76, v77
	v_max3_f32 v253, v253, v108, v109
	v_max3_f32 v239, v239, v78, v79
	v_max3_f32 v253, v253, v110, v111
	v_max3_f32 v239, v239, v80, v81
	v_max3_f32 v253, v253, v112, v113
	v_add_f32_e32 v254, 0x4259535f, v237
	v_cmp_gt_f32_e32 vcc, v239, v254
	s_cbranch_vccz .Lmla_nr0
	ds_bpermute_b32 v254, v203, v239
	s_waitcnt lgkmcnt(0)
	v_max_f32_e32 v254, v254, v254
	v_max_f32_e32 v239, v239, v254
	v_max_f32_e32 v254, v237, v237
	v_max_f32_e32 v239, v254, v239
	v_sub_f32_e32 v237, v237, v239
	v_mul_f32_e32 v237, 0x3e16c740, v237
	v_exp_f32_e32 v254, v237
	v_mov_b32_e32 v237, v239
	v_pk_mul_f32 v[64:65], v[64:65], v[254:255] op_sel_hi:[1,0]
	v_pk_mul_f32 v[62:63], v[62:63], v[254:255] op_sel_hi:[1,0]
	v_pk_mul_f32 v[60:61], v[60:61], v[254:255] op_sel_hi:[1,0]
	v_pk_mul_f32 v[58:59], v[58:59], v[254:255] op_sel_hi:[1,0]
	v_pk_mul_f32 v[56:57], v[56:57], v[254:255] op_sel_hi:[1,0]
	v_pk_mul_f32 v[54:55], v[54:55], v[254:255] op_sel_hi:[1,0]
	v_pk_mul_f32 v[52:53], v[52:53], v[254:255] op_sel_hi:[1,0]
	v_pk_mul_f32 v[50:51], v[50:51], v[254:255] op_sel_hi:[1,0]
	v_pk_mul_f32 v[48:49], v[48:49], v[254:255] op_sel_hi:[1,0]
	v_pk_mul_f32 v[46:47], v[46:47], v[254:255] op_sel_hi:[1,0]
	v_pk_mul_f32 v[44:45], v[44:45], v[254:255] op_sel_hi:[1,0]
	v_pk_mul_f32 v[42:43], v[42:43], v[254:255] op_sel_hi:[1,0]
	v_pk_mul_f32 v[40:41], v[40:41], v[254:255] op_sel_hi:[1,0]
	v_pk_mul_f32 v[38:39], v[38:39], v[254:255] op_sel_hi:[1,0]
	v_pk_mul_f32 v[36:37], v[36:37], v[254:255] op_sel_hi:[1,0]
	v_pk_mul_f32 v[34:35], v[34:35], v[254:255] op_sel_hi:[1,0]
	v_mul_f32_e32 v236, v236, v254

; DI unsigned pk2(float a, float b) { f32x2 v = {a, b}; bf16x2_t r = __builtin_convertvector(v, bf16x2_t); return __builtin_bit_cast(unsigned, r); }
; template <int DQK, bool BAND, int QT> ...
;     ...
;         const float mc = -m[qt] * cc;
;         float ls = 0.f;
; #pragma unroll
;         for (int a = 0; a < 2; ++a) {
; #pragma unroll
;           for (int r = 0; r < 16; ++r) { const float pv = __builtin_amdgcn_exp2f(fmaf(s[a][qt][r], cc, mc)); s[a][qt][r] = pv; ls += pv; }
; #pragma unroll
;           for (int s2 = 0; s2 < 2; ++s2) {
;             u32x4 pk;
;             pk.x = pk2(s[a][qt][8 * s2 + 0], s[a][qt][8 * s2 + 1]);
;             pk.y = pk2(s[a][qt][8 * s2 + 2], s[a][qt][8 * s2 + 3]);
;             pk.z = pk2(s[a][qt][8 * s2 + 4], s[a][qt][8 * s2 + 5]);
;             pk.w = pk2(s[a][qt][8 * s2 + 6], s[a][qt][8 * s2 + 7]);
;             pf[qt][a * 2 + s2] = __builtin_bit_cast(bf16x8, pk);
;           }
;         }
.Lmla_nostage:
	v_mul_f32_e32 v254, 0xbe16c740, v237
	v_mul_f32_e32 v255, 0xbe16c740, v238
	v_fmamk_f32 v82, v82, 0x3e16c740, v254
	v_fmamk_f32 v114, v114, 0x3e16c740, v255
	v_fmamk_f32 v83, v83, 0x3e16c740, v254
	v_fmamk_f32 v115, v115, 0x3e16c740, v255
	v_fmamk_f32 v84, v84, 0x3e16c740, v254
	v_fmamk_f32 v116, v116, 0x3e16c740, v255
	v_fmamk_f32 v85, v85, 0x3e16c740, v254
	v_fmamk_f32 v117, v117, 0x3e16c740, v255
	v_fmamk_f32 v86, v86, 0x3e16c740, v254
	v_fmamk_f32 v118, v118, 0x3e16c740, v255
	v_fmamk_f32 v87, v87, 0x3e16c740, v254
	v_fmamk_f32 v119, v119, 0x3e16c740, v255
	v_fmamk_f32 v88, v88, 0x3e16c740, v254
	v_fmamk_f32 v120, v120, 0x3e16c740, v255
	v_fmamk_f32 v89, v89, 0x3e16c740, v254
	v_fmamk_f32 v121, v121, 0x3e16c740, v255
	v_exp_f32_e32 v82, v82
	v_exp_f32_e32 v114, v114
	v_exp_f32_e32 v83, v83
	v_exp_f32_e32 v115, v115
	v_exp_f32_e32 v84, v84
	v_exp_f32_e32 v116, v116
	v_exp_f32_e32 v85, v85
	v_exp_f32_e32 v117, v117
	v_exp_f32_e32 v86, v86
	v_exp_f32_e32 v118, v118
	v_exp_f32_e32 v87, v87
	v_exp_f32_e32 v119, v119
	v_exp_f32_e32 v88, v88
	v_exp_f32_e32 v120, v120
	v_exp_f32_e32 v89, v89
	v_exp_f32_e32 v121, v121
	v_fmamk_f32 v90, v90, 0x3e16c740, v254
	v_fmamk_f32 v122, v122, 0x3e16c740, v255
	v_fmamk_f32 v91, v91, 0x3e16c740, v254
	v_fmamk_f32 v123, v123, 0x3e16c740, v255
	v_fmamk_f32 v92, v92, 0x3e16c740, v254
	v_fmamk_f32 v124, v124, 0x3e16c740, v255
	v_fmamk_f32 v93, v93, 0x3e16c740, v254
	v_fmamk_f32 v125, v125, 0x3e16c740, v255
	v_fmamk_f32 v94, v94, 0x3e16c740, v254
	v_fmamk_f32 v126, v126, 0x3e16c740, v255
	v_fmamk_f32 v95, v95, 0x3e16c740, v254
	v_fmamk_f32 v127, v127, 0x3e16c740, v255
	v_fmamk_f32 v96, v96, 0x3e16c740, v254
	v_fmamk_f32 v128, v128, 0x3e16c740, v255
	v_fmamk_f32 v97, v97, 0x3e16c740, v254
	v_fmamk_f32 v129, v129, 0x3e16c740, v255
	v_exp_f32_e32 v90, v90
	v_exp_f32_e32 v122, v122
	v_mov_b32_e32 v239, v82
	v_mov_b32_e32 v253, v114
	v_exp_f32_e32 v91, v91
	v_exp_f32_e32 v123, v123
	v_add_f32_e32 v239, v239, v83
	v_add_f32_e32 v253, v253, v115
	v_exp_f32_e32 v92, v92
	v_exp_f32_e32 v124, v124
	v_add_f32_e32 v239, v239, v84
	v_add_f32_e32 v253, v253, v116
	v_exp_f32_e32 v93, v93
	v_exp_f32_e32 v125, v125
	v_add_f32_e32 v239, v239, v85
	v_add_f32_e32 v253, v253, v117
	v_exp_f32_e32 v94, v94
	v_exp_f32_e32 v126, v126
	v_add_f32_e32 v239, v239, v86
	v_add_f32_e32 v253, v253, v118
	v_exp_f32_e32 v95, v95
	v_exp_f32_e32 v127, v127
	v_add_f32_e32 v239, v239, v87
	v_add_f32_e32 v253, v253, v119
	v_exp_f32_e32 v96, v96
	v_exp_f32_e32 v128, v128
	v_add_f32_e32 v239, v239, v88
	v_add_f32_e32 v253, v253, v120
	v_exp_f32_e32 v97, v97
	v_exp_f32_e32 v129, v129
	v_add_f32_e32 v239, v239, v89
	v_add_f32_e32 v253, v253, v121
	v_cvt_pk_bf16_f32 v82, v82, v83
	v_cvt_pk_bf16_f32 v114, v114, v115
	v_cvt_pk_bf16_f32 v83, v84, v85
	v_cvt_pk_bf16_f32 v115, v116, v117
	v_cvt_pk_bf16_f32 v84, v86, v87
	v_cvt_pk_bf16_f32 v116, v118, v119
	v_cvt_pk_bf16_f32 v85, v88, v89
	v_cvt_pk_bf16_f32 v117, v120, v121
	v_fmamk_f32 v66, v66, 0x3e16c740, v254
	v_fmamk_f32 v98, v98, 0x3e16c740, v255
	v_fmamk_f32 v67, v67, 0x3e16c740, v254
	v_fmamk_f32 v99, v99, 0x3e16c740, v255
	v_fmamk_f32 v68, v68, 0x3e16c740, v254
	v_fmamk_f32 v100, v100, 0x3e16c740, v255
	v_fmamk_f32 v69, v69, 0x3e16c740, v254
	v_fmamk_f32 v101, v101, 0x3e16c740, v255
	v_fmamk_f32 v70, v70, 0x3e16c740, v254
	v_fmamk_f32 v102, v102, 0x3e16c740, v255
	v_fmamk_f32 v71, v71, 0x3e16c740, v254
	v_fmamk_f32 v103, v103, 0x3e16c740, v255
	v_fmamk_f32 v72, v72, 0x3e16c740, v254
	v_fmamk_f32 v104, v104, 0x3e16c740, v255
	v_fmamk_f32 v73, v73, 0x3e16c740, v254
	v_fmamk_f32 v105, v105, 0x3e16c740, v255
	v_exp_f32_e32 v66, v66
	v_exp_f32_e32 v98, v98
	v_add_f32_e32 v239, v239, v90
	v_add_f32_e32 v253, v253, v122
	v_exp_f32_e32 v67, v67
	v_exp_f32_e32 v99, v99
	v_add_f32_e32 v239, v239, v91
	v_add_f32_e32 v253, v253, v123
	v_exp_f32_e32 v68, v68
	v_exp_f32_e32 v100, v100
	v_add_f32_e32 v239, v239, v92
	v_add_f32_e32 v253, v253, v124
	v_exp_f32_e32 v69, v69
	v_exp_f32_e32 v101, v101
	v_add_f32_e32 v239, v239, v93
	v_add_f32_e32 v253, v253, v125
	v_exp_f32_e32 v70, v70
	v_exp_f32_e32 v102, v102
	v_add_f32_e32 v239, v239, v94
	v_add_f32_e32 v253, v253, v126
	v_exp_f32_e32 v71, v71
	v_exp_f32_e32 v103, v103
	v_add_f32_e32 v239, v239, v95
	v_add_f32_e32 v253, v253, v127
	v_exp_f32_e32 v72, v72
	v_exp_f32_e32 v104, v104
	v_add_f32_e32 v239, v239, v96
	v_add_f32_e32 v253, v253, v128
	v_exp_f32_e32 v73, v73
	v_exp_f32_e32 v105, v105
	v_add_f32_e32 v239, v239, v97
	v_add_f32_e32 v253, v253, v129
	v_cvt_pk_bf16_f32 v90, v90, v91
	v_cvt_pk_bf16_f32 v122, v122, v123
	v_cvt_pk_bf16_f32 v91, v92, v93
	v_cvt_pk_bf16_f32 v123, v124, v125
	v_cvt_pk_bf16_f32 v92, v94, v95
	v_cvt_pk_bf16_f32 v124, v126, v127
	v_cvt_pk_bf16_f32 v93, v96, v97
	v_cvt_pk_bf16_f32 v125, v128, v129
	v_fmamk_f32 v74, v74, 0x3e16c740, v254
	v_fmamk_f32 v106, v106, 0x3e16c740, v255
	v_fmamk_f32 v75, v75, 0x3e16c740, v254
	v_fmamk_f32 v107, v107, 0x3e16c740, v255
	v_fmamk_f32 v76, v76, 0x3e16c740, v254
	v_fmamk_f32 v108, v108, 0x3e16c740, v255
	v_fmamk_f32 v77, v77, 0x3e16c740, v254
; #define MFMA(a, b, c) __builtin_amdgcn_mfma_f32_32x32x16_bf16((a), (b), (c), 0, 0, 0)
; DI unsigned pk2(float a, float b) { f32x2 v = {a, b}; bf16x2_t r = __builtin_convertvector(v, bf16x2_t); return __builtin_bit_cast(unsigned, r); }
; template <int DQK, bool BAND, int QT> ...
;     ...
;         const float mc = -m[qt] * cc;
;         float ls = 0.f;
; #pragma unroll
;         for (int a = 0; a < 2; ++a) {
; #pragma unroll
;           for (int r = 0; r < 16; ++r) { const float pv = __builtin_amdgcn_exp2f(fmaf(s[a][qt][r], cc, mc)); s[a][qt][r] = pv; ls += pv; }
; #pragma unroll
;           for (int s2 = 0; s2 < 2; ++s2) {
;             u32x4 pk;
;             pk.x = pk2(s[a][qt][8 * s2 + 0], s[a][qt][8 * s2 + 1]);
;             pk.y = pk2(s[a][qt][8 * s2 + 2], s[a][qt][8 * s2 + 3]);
;             pk.z = pk2(s[a][qt][8 * s2 + 4], s[a][qt][8 * s2 + 5]);
;             pk.w = pk2(s[a][qt][8 * s2 + 6], s[a][qt][8 * s2 + 7]);
;             pf[qt][a * 2 + s2] = __builtin_bit_cast(bf16x8, pk);
;           }
;         }
;         l[qt] += ls;
;       }
;       __builtin_amdgcn_s_setprio(0);
;       if (more) lstore(lds + ((it + 1) & 1) * ST);
; #pragma unroll
;       for (int ks = 0; ks < 4; ++ks) {
;         const bf16x8 v0 = *(const bf16x8*)(st + v_rd + ks * 32);
;         const bf16x8 v1 = *(const bf16x8*)(st + v_rd + 32 * LROW + ks * 32);
; #pragma unroll
;         for (int qt = 0; qt < QT; ++qt) {
;           o[0][qt] = MFMA(v0, pf[qt][ks], o[0][qt]);
;           o[1][qt] = MFMA(v1, pf[qt][ks], o[1][qt]);
;         }
;       }
;     } else {
;       if (more) lstore(lds + ((it + 1) & 1) * ST);
;     }
;     __syncthreads();
	v_fmamk_f32 v109, v109, 0x3e16c740, v255
	v_fmamk_f32 v78, v78, 0x3e16c740, v254
	v_fmamk_f32 v110, v110, 0x3e16c740, v255
	v_fmamk_f32 v79, v79, 0x3e16c740, v254
	v_fmamk_f32 v111, v111, 0x3e16c740, v255
	v_fmamk_f32 v80, v80, 0x3e16c740, v254
	v_fmamk_f32 v112, v112, 0x3e16c740, v255
	v_fmamk_f32 v81, v81, 0x3e16c740, v254
	v_fmamk_f32 v113, v113, 0x3e16c740, v255
	v_exp_f32_e32 v74, v74
	v_exp_f32_e32 v106, v106
	v_add_f32_e32 v239, v239, v66
	v_add_f32_e32 v253, v253, v98
	v_exp_f32_e32 v75, v75
	v_exp_f32_e32 v107, v107
	v_add_f32_e32 v239, v239, v67
	v_add_f32_e32 v253, v253, v99
	v_exp_f32_e32 v76, v76
	v_exp_f32_e32 v108, v108
	v_add_f32_e32 v239, v239, v68
	v_add_f32_e32 v253, v253, v100
	v_exp_f32_e32 v77, v77
	v_exp_f32_e32 v109, v109
	v_add_f32_e32 v239, v239, v69
	v_add_f32_e32 v253, v253, v101
	v_exp_f32_e32 v78, v78
	v_exp_f32_e32 v110, v110
	v_add_f32_e32 v239, v239, v70
	v_add_f32_e32 v253, v253, v102
	v_exp_f32_e32 v79, v79
	v_exp_f32_e32 v111, v111
	v_add_f32_e32 v239, v239, v71
	v_add_f32_e32 v253, v253, v103
	v_exp_f32_e32 v80, v80
	v_exp_f32_e32 v112, v112
	v_add_f32_e32 v239, v239, v72
	v_add_f32_e32 v253, v253, v104
	v_exp_f32_e32 v81, v81
	v_exp_f32_e32 v113, v113
	v_add_f32_e32 v239, v239, v73
	v_add_f32_e32 v253, v253, v105
	v_cvt_pk_bf16_f32 v66, v66, v67
	v_cvt_pk_bf16_f32 v98, v98, v99
	v_cvt_pk_bf16_f32 v67, v68, v69
	v_cvt_pk_bf16_f32 v99, v100, v101
	v_cvt_pk_bf16_f32 v68, v70, v71
	v_cvt_pk_bf16_f32 v100, v102, v103
	v_cvt_pk_bf16_f32 v69, v72, v73
	v_cvt_pk_bf16_f32 v101, v104, v105
	v_add_f32_e32 v239, v239, v74
	v_add_f32_e32 v253, v253, v106
	v_add_f32_e32 v239, v239, v75
	v_add_f32_e32 v253, v253, v107
	v_add_f32_e32 v239, v239, v76
	v_add_f32_e32 v253, v253, v108
	v_add_f32_e32 v239, v239, v77
	v_add_f32_e32 v253, v253, v109
	v_add_f32_e32 v239, v239, v78
	v_add_f32_e32 v253, v253, v110
	v_add_f32_e32 v239, v239, v79
	v_add_f32_e32 v253, v253, v111
	v_add_f32_e32 v239, v239, v80
	v_add_f32_e32 v253, v253, v112
	v_add_f32_e32 v239, v239, v81
	v_add_f32_e32 v253, v253, v113
	v_cvt_pk_bf16_f32 v74, v74, v75
	v_cvt_pk_bf16_f32 v106, v106, v107
	v_cvt_pk_bf16_f32 v75, v76, v77
	v_cvt_pk_bf16_f32 v107, v108, v109
	v_cvt_pk_bf16_f32 v76, v78, v79
	v_cvt_pk_bf16_f32 v108, v110, v111
	v_cvt_pk_bf16_f32 v77, v80, v81
	v_cvt_pk_bf16_f32 v109, v112, v113
	v_add_f32_e32 v236, v236, v239
	v_add_f32_e32 v207, v207, v253
	s_setprio 2
	ds_read_b128 v[86:89], v234 offset:13312
	ds_read_b128 v[94:97], v234 offset:17920
	ds_read_b128 v[70:73], v234 offset:13344
	ds_read_b128 v[78:81], v234 offset:17952
	ds_read_b128 v[118:121], v234 offset:13376
	ds_read_b128 v[126:129], v234 offset:17984
	ds_read_b128 v[102:105], v234 offset:13408
	ds_read_b128 v[110:113], v234 offset:18016
	s_waitcnt lgkmcnt(7)
	v_mfma_f32_32x32x16_bf16 v[50:65], v[86:89], v[82:85], v[50:65]
	v_mfma_f32_32x32x16_bf16 v[18:33], v[86:89], v[114:117], v[18:33]
	s_waitcnt lgkmcnt(6)
	v_mfma_f32_32x32x16_bf16 v[34:49], v[94:97], v[82:85], v[34:49]
	v_mfma_f32_32x32x16_bf16 v[2:17], v[94:97], v[114:117], v[2:17]
	s_add_i32 s7, s6, 64
	s_cmp_lt_u32 s7, s19
	s_cselect_b64 s[2:3], -1, 0
	s_cbranch_scc0 .Lmla_noloadp
	v_lshl_add_u64 v[254:255], s[94:95], 0, v[212:213]
	global_load_dwordx4 v[130:133], v[254:255], off
	v_lshl_add_u64 v[254:255], s[94:95], 0, v[214:215]
	global_load_dwordx4 v[134:137], v[254:255], off
	v_lshl_add_u64 v[254:255], s[94:95], 0, v[216:217]
	global_load_dwordx4 v[138:141], v[254:255], off
	v_lshl_add_u64 v[254:255], s[94:95], 0, v[208:209]
	global_load_dwordx4 v[146:149], v[254:255], off
	v_lshl_add_u64 v[254:255], s[94:95], 0, v[210:211]
	global_load_dwordx4 v[170:173], v[254:255], off
.Lmla_noloadp:
	v_lshl_add_u64 v[208:209], v[208:209], 0, s[76:77]
	v_lshl_add_u64 v[210:211], v[210:211], 0, s[76:77]
	v_lshl_add_u64 v[212:213], v[212:213], 0, s[84:85]
	v_lshl_add_u64 v[214:215], v[214:215], 0, s[84:85]
	v_lshl_add_u64 v[216:217], v[216:217], 0, s[84:85]
	s_waitcnt lgkmcnt(5)
	v_mfma_f32_32x32x16_bf16 v[50:65], v[70:73], v[90:93], v[50:65]
	v_mfma_f32_32x32x16_bf16 v[18:33], v[70:73], v[122:125], v[18:33]
	s_waitcnt lgkmcnt(4)
	v_mfma_f32_32x32x16_bf16 v[34:49], v[78:81], v[90:93], v[34:49]
	v_mfma_f32_32x32x16_bf16 v[2:17], v[78:81], v[122:125], v[2:17]
	s_waitcnt lgkmcnt(3)
	v_mfma_f32_32x32x16_bf16 v[50:65], v[118:121], v[66:69], v[50:65]
	v_mfma_f32_32x32x16_bf16 v[18:33], v[118:121], v[98:101], v[18:33]
	s_waitcnt lgkmcnt(2)
	v_mfma_f32_32x32x16_bf16 v[34:49], v[126:129], v[66:69], v[34:49]
	v_mfma_f32_32x32x16_bf16 v[2:17], v[126:129], v[98:101], v[2:17]
	s_bitcmp1_b32 s1, 0
	s_cselect_b32 s7, -1, 1
	s_mulk_i32 s7, 0x5800
	v_add_u32_e32 v235, s7, v235
	v_add_u32_e32 v234, s7, v234
	s_add_i32 s1, s1, 1
	s_add_i32 s6, s6, 64
	s_waitcnt lgkmcnt(0)
	s_barrier
	v_mfma_f32_32x32x16_bf16 v[50:65], v[102:105], v[74:77], v[50:65]
	v_mfma_f32_32x32x16_bf16 v[18:33], v[102:105], v[106:109], v[18:33]
	v_mfma_f32_32x32x16_bf16 v[34:49], v[110:113], v[74:77], v[34:49]
	v_mfma_f32_32x32x16_bf16 v[2:17], v[110:113], v[106:109], v[2:17]
	s_cmp_lg_u32 s21, s1
	s_cbranch_scc1 .Lmla_top
	s_setprio 0
	s_branch .LBB0_663
